# E48: grid barrier - L1 acquire invalidate issued before the arrival atomic so it overlaps the atomic round trip and is off the XCD leader's write-back chain
# speedup vs baseline: 1.0689x; 1.0689x over previous
; DI unsigned xb_ld(unsigned* p)              { return __hip_atomic_load(p, __ATOMIC_RELAXED, __HIP_MEMORY_SCOPE_AGENT); }
; DI unsigned xb_add(unsigned* p, unsigned v) { return __hip_atomic_fetch_add(p, v, __ATOMIC_RELAXED, __HIP_MEMORY_SCOPE_AGENT); }
; #define XB_SPIN(cond, bar) do { unsigned _sp = 0; while (cond) { __builtin_amdgcn_s_sleep(1); \
;     if ((++_sp & 255u) == 0u) { if (xb_ld(&(bar)[XB_TMO])) break; if (_sp > XB_SPIN_CAP) { atomicAdd(&(bar)[XB_TMO], 1u); break; } } } } while (0)
; DI void xcd_barrier(const XcdBarrier& b) {
;     ...
;         const unsigned old = xb_add(&bar[XB_XSUB(b.x)], 1u);
;         const unsigned gen = old / nloc;
;         if (old + 1u == (gen + 1u) * nloc) {
;             __builtin_amdgcn_fence(__ATOMIC_RELEASE, "agent");
;             asm volatile("s_waitcnt vmcnt(0)" ::: "memory");
;             const unsigned og = xb_add(&bar[XB_TOP], 1u);
;             const unsigned tg = og / nx;
;             if (og + 1u == (tg + 1u) * nx) xb_add(&bar[XB_TOPGEN], 1u);
;             else XB_SPIN(xb_ld(&bar[XB_TOPGEN]) == tg, bar);
;             __builtin_amdgcn_fence(__ATOMIC_ACQUIRE, "agent");
;             xb_add(&bar[XB_XGEN(b.x)], 1u);
;             asm volatile("s_waitcnt vmcnt(0)" ::: "memory");
;         } else {
;             XB_SPIN(xb_ld(&bar[XB_XGEN(b.x)]) == gen, bar);
;             __builtin_amdgcn_fence(__ATOMIC_ACQUIRE, "agent");
;             asm volatile("s_waitcnt vmcnt(0)" ::: "memory");
;         }
.LBB0_58:
	s_lshl_b32 s8, s3, 8
	s_add_u32 s8, s40, s8
	s_addc_u32 s9, s41, 0
	v_mov_b32_e32 v1, 0x1000
	v_mov_b32_e32 v3, 1
	buffer_inv sc1
	global_atomic_add v3, v1, v3, s[8:9] offset:1024 sc0
	v_cvt_f32_u32_e32 v1, v2
	v_sub_u32_e32 v4, 0, v2
	s_add_u32 s8, s8, 0x2400
	s_addc_u32 s9, s9, 0
	v_rcp_iflag_f32_e32 v1, v1
	s_nop 0
	v_mul_f32_e32 v1, 0x4f7ffffe, v1
	v_cvt_u32_f32_e32 v1, v1
	v_mul_lo_u32 v4, v4, v1
	v_mul_hi_u32 v4, v1, v4
	v_add_u32_e32 v1, v1, v4
	s_waitcnt vmcnt(0)
	v_mul_hi_u32 v1, v3, v1
	v_mul_lo_u32 v4, v1, v2
	v_sub_u32_e32 v4, v3, v4
	v_add_u32_e32 v5, 1, v1
	v_cmp_ge_u32_e32 vcc, v4, v2
	v_add_u32_e32 v3, 1, v3
	s_nop 0
	v_cndmask_b32_e32 v1, v1, v5, vcc
	v_sub_u32_e32 v5, v4, v2
	v_cndmask_b32_e32 v4, v4, v5, vcc
	v_add_u32_e32 v5, 1, v1
	v_cmp_ge_u32_e32 vcc, v4, v2
	s_nop 1
	v_cndmask_b32_e32 v1, v1, v5, vcc
	v_mul_lo_u32 v4, v2, v1
	v_add_u32_e32 v2, v4, v2
	v_cmp_ne_u32_e32 vcc, v3, v2
	s_and_saveexec_b64 s[10:11], vcc
	s_xor_b64 s[10:11], exec, s[10:11]
	s_cbranch_execz .LBB0_72
	s_add_u32 s8, s6, 0x3200
	s_addc_u32 s9, s7, 0
	s_waitcnt lgkmcnt(0)
	v_mad_u32_u24 v1, v1, v0, v0
	v_mov_b32_e32 v0, 0
	global_load_dword v2, v0, s[8:9] sc1
	s_waitcnt vmcnt(0)
	v_cmp_lt_u32_e32 vcc, v2, v1
	s_and_saveexec_b64 s[12:13], vcc
	s_cbranch_execz .LBB0_71
	s_mov_b32 s24, 1
	s_mov_b64 s[14:15], 0
	s_branch .LBB0_62

; DI unsigned xb_ld(unsigned* p)              { return __hip_atomic_load(p, __ATOMIC_RELAXED, __HIP_MEMORY_SCOPE_AGENT); }
; DI unsigned xb_add(unsigned* p, unsigned v) { return __hip_atomic_fetch_add(p, v, __ATOMIC_RELAXED, __HIP_MEMORY_SCOPE_AGENT); }
; #define XB_SPIN(cond, bar) do { unsigned _sp = 0; while (cond) { __builtin_amdgcn_s_sleep(1); \
;     if ((++_sp & 255u) == 0u) { if (xb_ld(&(bar)[XB_TMO])) break; if (_sp > XB_SPIN_CAP) { atomicAdd(&(bar)[XB_TMO], 1u); break; } } } } while (0)
; DI void xcd_barrier(const XcdBarrier& b) {
;     ...
;         const unsigned old = xb_add(&bar[XB_XSUB(b.x)], 1u);
;         const unsigned gen = old / nloc;
;         if (old + 1u == (gen + 1u) * nloc) {
;             __builtin_amdgcn_fence(__ATOMIC_RELEASE, "agent");
;             asm volatile("s_waitcnt vmcnt(0)" ::: "memory");
;             const unsigned og = xb_add(&bar[XB_TOP], 1u);
;             const unsigned tg = og / nx;
;             if (og + 1u == (tg + 1u) * nx) xb_add(&bar[XB_TOPGEN], 1u);
;             else XB_SPIN(xb_ld(&bar[XB_TOPGEN]) == tg, bar);
;             __builtin_amdgcn_fence(__ATOMIC_ACQUIRE, "agent");
;             xb_add(&bar[XB_XGEN(b.x)], 1u);
;             asm volatile("s_waitcnt vmcnt(0)" ::: "memory");
;         } else {
;             XB_SPIN(xb_ld(&bar[XB_XGEN(b.x)]) == gen, bar);
;             __builtin_amdgcn_fence(__ATOMIC_ACQUIRE, "agent");
;             asm volatile("s_waitcnt vmcnt(0)" ::: "memory");
;         }
; __global__ void __launch_bounds__(512, 2) fwd_kernel(Args a_byval) {
;     ...
;             if (step == 0 || step == 2 || step == 4) xcd_barrier(bar);
.LBB0_1005:
	v_readlane_b32 s4, v253, 52
	v_readlane_b32 s5, v253, 53
	v_cvt_f32_u32_e32 v1, v2
	v_sub_u32_e32 v4, 0, v2
	v_rcp_iflag_f32_e32 v1, v1
	s_nop 1
	buffer_inv sc1
	global_atomic_add v3, v173, v237, s[4:5] sc0
	v_mul_f32_e32 v1, 0x4f7ffffe, v1
	v_cvt_u32_f32_e32 v1, v1
	v_mul_lo_u32 v4, v4, v1
	v_mul_hi_u32 v4, v1, v4
	v_add_u32_e32 v1, v1, v4
	s_waitcnt vmcnt(0)
	v_mul_hi_u32 v1, v3, v1
	v_mul_lo_u32 v4, v1, v2
	v_sub_u32_e32 v4, v3, v4
	v_add_u32_e32 v5, 1, v1
	v_cmp_ge_u32_e32 vcc, v4, v2
	v_add_u32_e32 v3, 1, v3
	s_nop 0
	v_cndmask_b32_e32 v1, v1, v5, vcc
	v_sub_u32_e32 v5, v4, v2
	v_cndmask_b32_e32 v4, v4, v5, vcc
	v_add_u32_e32 v5, 1, v1
	v_cmp_ge_u32_e32 vcc, v4, v2
	s_nop 1
	v_cndmask_b32_e32 v1, v1, v5, vcc
	v_mul_lo_u32 v4, v2, v1
	v_add_u32_e32 v2, v4, v2
	v_cmp_ne_u32_e32 vcc, v3, v2
	s_and_saveexec_b64 s[4:5], vcc
	s_xor_b64 s[4:5], exec, s[4:5]
	s_cbranch_execz .LBB0_1019
	s_add_u32 s6, s62, 0x3200
	s_addc_u32 s7, s63, 0
	s_waitcnt lgkmcnt(0)
	v_mad_u32_u24 v1, v1, v0, v0
	s_nop 3
	global_load_dword v0, v173, s[6:7] sc1
	s_waitcnt vmcnt(0)
	v_cmp_lt_u32_e32 vcc, v0, v1
	s_and_saveexec_b64 s[6:7], vcc
	s_cbranch_execz .LBB0_1018
	s_mov_b32 s18, 1
	s_mov_b64 s[8:9], 0
	s_branch .LBB0_1009
